# attention tile loop: the eight exec-masked bias look-ups (branch + LDS read + wait each) replaced by eight back-to-back LDS reads, one wait and masked selects; same per-element operations
# speedup vs baseline: 1.0104x; 1.0102x over previous
; __device__ __forceinline__ void phase_na_attn(const Fr& F) {
;     ...
;                     const int koff = nb ? lo : 32 * sub;
;                     f32x4 Sx[2];
; #pragma unroll
;                     for (int st = 0; st < 2; ++st) { Sx[st] = (f32x4){0.f, 0.f, 0.f, 0.f};
; #pragma unroll
;                         for (int ds = 0; ds < 2; ++ds) { const bf16x8 Kf = *(const bf16x8*)(Kl + (koff + 16 * st + l15) * KST + 32 * ds + 8 * lq);
;                             Sx[st] = __builtin_amdgcn_mfma_f32_16x16x32_bf16(Kf, Qf[ds], Sx[st], 0, 0, 0); } }
;                     float pv[2][4];
; #pragma unroll
;                     for (int st = 0; st < 2; ++st)
; #pragma unroll
;                         for (int reg = 0; reg < 4; ++reg) {
;                             if (nb) { const int bo = boff[st][reg]; pv[st][reg] = bo >= 0 ? __expf(Sx[st][reg] + rpbT[(rr - gi + 7) * 31 + bo]) : 0.f; }
;                             else pv[st][reg] = __expf(Sx[st][reg]); }
.LBB0_1087:
	s_and_b64 s[24:25], s[54:55], exec
	s_cselect_b32 s86, s75, s85
	v_add_u32_e32 v48, s86, v61
	v_mad_u64_u32 v[108:109], s[24:25], v48, s73, v[66:67]
	ds_read_b128 v[48:51], v108
	ds_read_b128 v[52:55], v108 offset:64
	ds_read_b128 v[104:107], v108 offset:2304
	ds_read_b128 v[108:111], v108 offset:2368
	s_mov_b64 s[24:25], -1
	s_waitcnt lgkmcnt(3)
	v_mfma_f32_16x16x32_bf16 v[48:51], v[48:51], v[28:31], 0
	s_and_b64 vcc, exec, s[56:57]
	s_waitcnt lgkmcnt(1)
	v_mfma_f32_16x16x32_bf16 v[104:107], v[104:107], v[28:31], 0
	v_mfma_f32_16x16x32_bf16 v[52:55], v[52:55], v[24:27], v[48:51]
	s_waitcnt lgkmcnt(0)
	v_mfma_f32_16x16x32_bf16 v[48:51], v[108:111], v[24:27], v[104:107]
	s_cbranch_vccnz .Lattn_ctx1
	ds_read_b32 v112, v95 offset:50020
	ds_read_b32 v113, v96 offset:50020
	ds_read_b32 v114, v97 offset:50020
	ds_read_b32 v115, v98 offset:50020
	ds_read_b32 v116, v99 offset:50020
	ds_read_b32 v117, v100 offset:50020
	ds_read_b32 v118, v101 offset:50020
	ds_read_b32 v119, v102 offset:50020
	s_waitcnt lgkmcnt(0)
	v_add_f32_e32 v112, v52, v112
	v_add_f32_e32 v113, v53, v113
	v_add_f32_e32 v114, v54, v114
	v_add_f32_e32 v115, v55, v115
	v_add_f32_e32 v116, v48, v116
	v_add_f32_e32 v117, v49, v117
	v_add_f32_e32 v118, v50, v118
	v_add_f32_e32 v119, v51, v119
	v_mul_f32_e32 v112, 0x3fb8aa3b, v112
	v_mul_f32_e32 v113, 0x3fb8aa3b, v113
	v_mul_f32_e32 v114, 0x3fb8aa3b, v114
	v_mul_f32_e32 v115, 0x3fb8aa3b, v115
	v_mul_f32_e32 v116, 0x3fb8aa3b, v116
	v_mul_f32_e32 v117, 0x3fb8aa3b, v117
	v_mul_f32_e32 v118, 0x3fb8aa3b, v118
	v_mul_f32_e32 v119, 0x3fb8aa3b, v119
	v_exp_f32_e32 v112, v112
	v_exp_f32_e32 v113, v113
	v_exp_f32_e32 v114, v114
	v_exp_f32_e32 v115, v115
	v_exp_f32_e32 v116, v116
	v_exp_f32_e32 v117, v117
	v_exp_f32_e32 v118, v118
	v_exp_f32_e32 v119, v119
	v_cndmask_b32_e64 v103, 0, v112, s[8:9]
	v_cndmask_b32_e64 v52, 0, v113, s[10:11]
	v_cndmask_b32_e64 v53, 0, v114, s[12:13]
	v_cndmask_b32_e64 v54, 0, v115, s[14:15]
	v_cndmask_b32_e64 v55, 0, v116, s[16:17]
	v_cndmask_b32_e64 v48, 0, v117, s[18:19]
	v_cndmask_b32_e64 v49, 0, v118, s[20:21]
	v_cndmask_b32_e64 v50, 0, v119, s[22:23]
	s_branch .LBB0_1086
.Lattn_ctx1:
	s_nop 7
	v_mul_f32_e32 v103, 0x3fb8aa3b, v52
	v_mul_f32_e32 v52, 0x3fb8aa3b, v53
	v_mul_f32_e32 v53, 0x3fb8aa3b, v54
	v_mul_f32_e32 v54, 0x3fb8aa3b, v55
	v_mul_f32_e32 v55, 0x3fb8aa3b, v48
	v_mul_f32_e32 v48, 0x3fb8aa3b, v49
	v_mul_f32_e32 v49, 0x3fb8aa3b, v50
	v_mul_f32_e32 v50, 0x3fb8aa3b, v51
	v_exp_f32_e32 v103, v103
	v_exp_f32_e32 v52, v52
	v_exp_f32_e32 v53, v53
	v_exp_f32_e32 v54, v54
	v_exp_f32_e32 v55, v55
	v_exp_f32_e32 v48, v48
	v_exp_f32_e32 v49, v49
	v_exp_f32_e32 v50, v50
	s_branch .LBB0_1086

; __device__ __forceinline__ void phase_na_attn(const Fr& F) {
;     ...
;                     const int koff = nb ? lo : 32 * sub;
;                     f32x4 Sx[2];
; #pragma unroll
;                     for (int st = 0; st < 2; ++st) { Sx[st] = (f32x4){0.f, 0.f, 0.f, 0.f};
; #pragma unroll
;                         for (int ds = 0; ds < 2; ++ds) { const bf16x8 Kf = *(const bf16x8*)(Kl + (koff + 16 * st + l15) * KST + 32 * ds + 8 * lq);
;                             Sx[st] = __builtin_amdgcn_mfma_f32_16x16x32_bf16(Kf, Qf[ds], Sx[st], 0, 0, 0); } }
;                     float pv[2][4];
; #pragma unroll
;                     for (int st = 0; st < 2; ++st)
; #pragma unroll
;                         for (int reg = 0; reg < 4; ++reg) {
;                             if (nb) { const int bo = boff[st][reg]; pv[st][reg] = bo >= 0 ? __expf(Sx[st][reg] + rpbT[(rr - gi + 7) * 31 + bo]) : 0.f; }
;                             else pv[st][reg] = __expf(Sx[st][reg]); }
.LBB0_1148:
	s_and_b64 s[24:25], s[54:55], exec
	s_cselect_b32 s86, s75, s85
	v_add_u32_e32 v48, s86, v61
	v_mad_u64_u32 v[108:109], s[24:25], v48, s73, v[66:67]
	ds_read_b128 v[48:51], v108 offset:18432
	ds_read_b128 v[52:55], v108 offset:18496
	ds_read_b128 v[104:107], v108 offset:20736
	ds_read_b128 v[108:111], v108 offset:20800
	s_mov_b64 s[24:25], -1
	s_waitcnt lgkmcnt(3)
	v_mfma_f32_16x16x32_bf16 v[48:51], v[48:51], v[28:31], 0
	s_and_b64 vcc, exec, s[56:57]
	s_waitcnt lgkmcnt(1)
	v_mfma_f32_16x16x32_bf16 v[104:107], v[104:107], v[28:31], 0
	v_mfma_f32_16x16x32_bf16 v[52:55], v[52:55], v[24:27], v[48:51]
	s_waitcnt lgkmcnt(0)
	v_mfma_f32_16x16x32_bf16 v[48:51], v[108:111], v[24:27], v[104:107]
	s_cbranch_vccnz .Lattn_ctx0
	ds_read_b32 v112, v95 offset:50020
	ds_read_b32 v113, v96 offset:50020
	ds_read_b32 v114, v97 offset:50020
	ds_read_b32 v115, v98 offset:50020
	ds_read_b32 v116, v99 offset:50020
	ds_read_b32 v117, v100 offset:50020
	ds_read_b32 v118, v101 offset:50020
	ds_read_b32 v119, v102 offset:50020
	s_waitcnt lgkmcnt(0)
	v_add_f32_e32 v112, v52, v112
	v_add_f32_e32 v113, v53, v113
	v_add_f32_e32 v114, v54, v114
	v_add_f32_e32 v115, v55, v115
	v_add_f32_e32 v116, v48, v116
	v_add_f32_e32 v117, v49, v117
	v_add_f32_e32 v118, v50, v118
	v_add_f32_e32 v119, v51, v119
	v_mul_f32_e32 v112, 0x3fb8aa3b, v112
	v_mul_f32_e32 v113, 0x3fb8aa3b, v113
	v_mul_f32_e32 v114, 0x3fb8aa3b, v114
	v_mul_f32_e32 v115, 0x3fb8aa3b, v115
	v_mul_f32_e32 v116, 0x3fb8aa3b, v116
	v_mul_f32_e32 v117, 0x3fb8aa3b, v117
	v_mul_f32_e32 v118, 0x3fb8aa3b, v118
	v_mul_f32_e32 v119, 0x3fb8aa3b, v119
	v_exp_f32_e32 v112, v112
	v_exp_f32_e32 v113, v113
	v_exp_f32_e32 v114, v114
	v_exp_f32_e32 v115, v115
	v_exp_f32_e32 v116, v116
	v_exp_f32_e32 v117, v117
	v_exp_f32_e32 v118, v118
	v_exp_f32_e32 v119, v119
	v_cndmask_b32_e64 v103, 0, v112, s[8:9]
	v_cndmask_b32_e64 v52, 0, v113, s[10:11]
	v_cndmask_b32_e64 v53, 0, v114, s[12:13]
	v_cndmask_b32_e64 v54, 0, v115, s[14:15]
	v_cndmask_b32_e64 v55, 0, v116, s[16:17]
	v_cndmask_b32_e64 v48, 0, v117, s[18:19]
	v_cndmask_b32_e64 v49, 0, v118, s[20:21]
	v_cndmask_b32_e64 v50, 0, v119, s[22:23]
	s_branch .LBB0_1147
